# rs_prepass (up-proj, final): the 16 partial sums of squares per row loaded up front and added in the original order behind counted waits (hipcc waited for each load); plus hand-written final rmsnorm,
# speedup vs baseline: 1.0113x; 1.0021x over previous
; template <class Sched>
; __device__ __forceinline__ RsTable rs_prepass(PG8_LAS unsigned char* lds_spare, const float* ssp, const Sched& S, int tid) {
;     ...
;     const int row = tid & 255, half = tid >> 8;
; #pragma unroll
;     for (int k = 0; k < 4; ++k) {
;         if (T.pm[k] < 0) continue;
;         const float* p = ssp + (size_t)(16 * half) * 16384 + T.pm[k] * 256 + row; float s = 0.f;
; #pragma unroll
;         for (int q = 0; q < 16; ++q) s += p[(size_t)q * 16384];
;         part[half * 256 + row] = s;
;         __syncthreads();
;         if (half == 0) tab[k * 256 + row] = rsqrtf((part[row] + part[256 + row]) * (1.0f / 2048.0f) + 1e-6f);
;         __syncthreads();
.LBB0_455:
	v_lshl_add_u32 v5, s16, 6, v1
	v_ashrrev_i32_e32 v2, 4, v5
	v_and_b32_e32 v2, -16, v2
	v_ashrrev_i32_e32 v3, 31, v2
	v_lshlrev_b64 v[2:3], 16, v[2:3]
	v_lshl_add_u64 v[2:3], s[0:1], 0, v[2:3]
	v_lshlrev_b32_sdwa v6, v198, v5 dst_sel:DWORD dst_unused:UNUSED_PAD src0_sel:DWORD src1_sel:BYTE_0
	v_mov_b32_e32 v7, v0
	v_lshl_add_u64 v[2:3], v[2:3], 0, v[6:7]
	s_mov_b64 s[0:1], 0x1fe00000
	v_lshlrev_b32_e32 v4, 2, v5
	v_readlane_b32 s2, v251, 23
	v_lshl_add_u64 v[2:3], v[2:3], 0, s[0:1]
	v_readlane_b32 s0, v251, 24
	s_movk_i32 s1, 0x100
	v_add_u32_e32 v1, s2, v4
	v_add_u32_e32 v4, s0, v4
	v_cmp_gt_u32_e64 s[6:7], s1, v5
	s_cmp_gt_i32 s15, -1
	v_add_u32_e32 v5, s0, v6
	s_cbranch_scc0 .LBB0_463
	s_lshl_b32 s56, s15, 8
	v_lshl_add_u64 v[6:7], s[56:57], 2, v[2:3]
	global_load_dword v20, v[6:7], off
	v_add_co_u32_e32 v36, vcc, 0x10000, v6
	s_nop 1
	v_addc_co_u32_e32 v37, vcc, 0, v7, vcc
	global_load_dword v21, v[36:37], off
	v_add_co_u32_e32 v36, vcc, 0x20000, v6
	s_nop 1
	v_addc_co_u32_e32 v37, vcc, 0, v7, vcc
	global_load_dword v22, v[36:37], off
	v_add_co_u32_e32 v36, vcc, 0x30000, v6
	s_nop 1
	v_addc_co_u32_e32 v37, vcc, 0, v7, vcc
	global_load_dword v23, v[36:37], off
	v_add_co_u32_e32 v36, vcc, 0x40000, v6
	s_nop 1
	v_addc_co_u32_e32 v37, vcc, 0, v7, vcc
	global_load_dword v24, v[36:37], off
	v_add_co_u32_e32 v36, vcc, 0x50000, v6
	s_nop 1
	v_addc_co_u32_e32 v37, vcc, 0, v7, vcc
	global_load_dword v25, v[36:37], off
	v_add_co_u32_e32 v36, vcc, 0x60000, v6
	s_nop 1
	v_addc_co_u32_e32 v37, vcc, 0, v7, vcc
	global_load_dword v26, v[36:37], off
	v_add_co_u32_e32 v36, vcc, 0x70000, v6
	s_nop 1
	v_addc_co_u32_e32 v37, vcc, 0, v7, vcc
	global_load_dword v27, v[36:37], off
	v_add_co_u32_e32 v36, vcc, 0x80000, v6
	s_nop 1
	v_addc_co_u32_e32 v37, vcc, 0, v7, vcc
	global_load_dword v28, v[36:37], off
	v_add_co_u32_e32 v36, vcc, 0x90000, v6
	s_nop 1
	v_addc_co_u32_e32 v37, vcc, 0, v7, vcc
	global_load_dword v29, v[36:37], off
	v_add_co_u32_e32 v36, vcc, 0xa0000, v6
	s_nop 1
	v_addc_co_u32_e32 v37, vcc, 0, v7, vcc
	global_load_dword v30, v[36:37], off
	v_add_co_u32_e32 v36, vcc, 0xb0000, v6
	s_nop 1
	v_addc_co_u32_e32 v37, vcc, 0, v7, vcc
	global_load_dword v31, v[36:37], off
	v_add_co_u32_e32 v36, vcc, 0xc0000, v6
	s_nop 1
	v_addc_co_u32_e32 v37, vcc, 0, v7, vcc
	global_load_dword v32, v[36:37], off
	v_add_co_u32_e32 v36, vcc, 0xd0000, v6
	s_nop 1
	v_addc_co_u32_e32 v37, vcc, 0, v7, vcc
	global_load_dword v33, v[36:37], off
	v_add_co_u32_e32 v36, vcc, 0xe0000, v6
	s_nop 1
	v_addc_co_u32_e32 v37, vcc, 0, v7, vcc
	global_load_dword v34, v[36:37], off
	v_add_co_u32_e32 v36, vcc, 0xf0000, v6
	s_nop 1
	v_addc_co_u32_e32 v37, vcc, 0, v7, vcc
	global_load_dword v35, v[36:37], off
	s_waitcnt vmcnt(15)
	v_add_f32_e32 v6, 0, v20
	s_waitcnt vmcnt(14)
	v_add_f32_e32 v6, v6, v21
	s_waitcnt vmcnt(13)
	v_add_f32_e32 v6, v6, v22
	s_waitcnt vmcnt(12)
	v_add_f32_e32 v6, v6, v23
	s_waitcnt vmcnt(11)
	v_add_f32_e32 v6, v6, v24
	s_waitcnt vmcnt(10)
	v_add_f32_e32 v6, v6, v25
	s_waitcnt vmcnt(9)
	v_add_f32_e32 v6, v6, v26
	s_waitcnt vmcnt(8)
	v_add_f32_e32 v6, v6, v27
	s_waitcnt vmcnt(7)
	v_add_f32_e32 v6, v6, v28
	s_waitcnt vmcnt(6)
	v_add_f32_e32 v6, v6, v29
	s_waitcnt vmcnt(5)
	v_add_f32_e32 v6, v6, v30
	s_waitcnt vmcnt(4)
	v_add_f32_e32 v6, v6, v31
	s_waitcnt vmcnt(3)
	v_add_f32_e32 v6, v6, v32
	s_waitcnt vmcnt(2)
	v_add_f32_e32 v6, v6, v33
	s_waitcnt vmcnt(1)
	v_add_f32_e32 v6, v6, v34
	s_waitcnt vmcnt(0)
	v_add_f32_e32 v6, v6, v35
	ds_write_b32 v4, v6
	s_waitcnt lgkmcnt(0)
	s_barrier
	s_and_saveexec_b64 s[0:1], s[6:7]
	s_cbranch_execz .LBB0_458
	ds_read_b32 v6, v5
	ds_read_b32 v7, v4 offset:1024
	s_mov_b32 s2, 0x800000
	s_waitcnt lgkmcnt(0)
	v_add_f32_e32 v6, v6, v7
	v_fmamk_f32 v6, v6, 0x3a000000, v192
	v_mul_f32_e32 v7, 0x4b800000, v6
	v_cmp_gt_f32_e32 vcc, s2, v6
	s_nop 1
	v_cndmask_b32_e32 v6, v6, v7, vcc
	v_rsq_f32_e32 v6, v6
	s_nop 0
	v_mul_f32_e32 v7, 0x45800000, v6
	v_cndmask_b32_e32 v6, v6, v7, vcc
	ds_write_b32 v1, v6

; template <class Sched>
; __device__ __forceinline__ RsTable rs_prepass(PG8_LAS unsigned char* lds_spare, const float* ssp, const Sched& S, int tid) {
;     ...
;         if (T.pm[k] < 0) continue;
;         const float* p = ssp + (size_t)(16 * half) * 16384 + T.pm[k] * 256 + row; float s = 0.f;
; #pragma unroll
;         for (int q = 0; q < 16; ++q) s += p[(size_t)q * 16384];
;         part[half * 256 + row] = s;
;         __syncthreads();
;         if (half == 0) tab[k * 256 + row] = rsqrtf((part[row] + part[256 + row]) * (1.0f / 2048.0f) + 1e-6f);
;         __syncthreads();
.LBB0_460:
	s_lshl_b32 s56, s9, 8
	v_lshl_add_u64 v[6:7], s[56:57], 2, v[2:3]
	global_load_dword v20, v[6:7], off
	v_add_co_u32_e32 v36, vcc, 0x10000, v6
	s_nop 1
	v_addc_co_u32_e32 v37, vcc, 0, v7, vcc
	global_load_dword v21, v[36:37], off
	v_add_co_u32_e32 v36, vcc, 0x20000, v6
	s_nop 1
	v_addc_co_u32_e32 v37, vcc, 0, v7, vcc
	global_load_dword v22, v[36:37], off
	v_add_co_u32_e32 v36, vcc, 0x30000, v6
	s_nop 1
	v_addc_co_u32_e32 v37, vcc, 0, v7, vcc
	global_load_dword v23, v[36:37], off
	v_add_co_u32_e32 v36, vcc, 0x40000, v6
	s_nop 1
	v_addc_co_u32_e32 v37, vcc, 0, v7, vcc
	global_load_dword v24, v[36:37], off
	v_add_co_u32_e32 v36, vcc, 0x50000, v6
	s_nop 1
	v_addc_co_u32_e32 v37, vcc, 0, v7, vcc
	global_load_dword v25, v[36:37], off
	v_add_co_u32_e32 v36, vcc, 0x60000, v6
	s_nop 1
	v_addc_co_u32_e32 v37, vcc, 0, v7, vcc
	global_load_dword v26, v[36:37], off
	v_add_co_u32_e32 v36, vcc, 0x70000, v6
	s_nop 1
	v_addc_co_u32_e32 v37, vcc, 0, v7, vcc
	global_load_dword v27, v[36:37], off
	v_add_co_u32_e32 v36, vcc, 0x80000, v6
	s_nop 1
	v_addc_co_u32_e32 v37, vcc, 0, v7, vcc
	global_load_dword v28, v[36:37], off
	v_add_co_u32_e32 v36, vcc, 0x90000, v6
	s_nop 1
	v_addc_co_u32_e32 v37, vcc, 0, v7, vcc
	global_load_dword v29, v[36:37], off
	v_add_co_u32_e32 v36, vcc, 0xa0000, v6
	s_nop 1
	v_addc_co_u32_e32 v37, vcc, 0, v7, vcc
	global_load_dword v30, v[36:37], off
	v_add_co_u32_e32 v36, vcc, 0xb0000, v6
	s_nop 1
	v_addc_co_u32_e32 v37, vcc, 0, v7, vcc
	global_load_dword v31, v[36:37], off
	v_add_co_u32_e32 v36, vcc, 0xc0000, v6
	s_nop 1
	v_addc_co_u32_e32 v37, vcc, 0, v7, vcc
	global_load_dword v32, v[36:37], off
	v_add_co_u32_e32 v36, vcc, 0xd0000, v6
	s_nop 1
	v_addc_co_u32_e32 v37, vcc, 0, v7, vcc
	global_load_dword v33, v[36:37], off
	v_add_co_u32_e32 v36, vcc, 0xe0000, v6
	s_nop 1
	v_addc_co_u32_e32 v37, vcc, 0, v7, vcc
	global_load_dword v34, v[36:37], off
	v_add_co_u32_e32 v36, vcc, 0xf0000, v6
	s_nop 1
	v_addc_co_u32_e32 v37, vcc, 0, v7, vcc
	global_load_dword v35, v[36:37], off
	s_waitcnt vmcnt(15)
	v_add_f32_e32 v6, 0, v20
	s_waitcnt vmcnt(14)
	v_add_f32_e32 v6, v6, v21
	s_waitcnt vmcnt(13)
	v_add_f32_e32 v6, v6, v22
	s_waitcnt vmcnt(12)
	v_add_f32_e32 v6, v6, v23
	s_waitcnt vmcnt(11)
	v_add_f32_e32 v6, v6, v24
	s_waitcnt vmcnt(10)
	v_add_f32_e32 v6, v6, v25
	s_waitcnt vmcnt(9)
	v_add_f32_e32 v6, v6, v26
	s_waitcnt vmcnt(8)
	v_add_f32_e32 v6, v6, v27
	s_waitcnt vmcnt(7)
	v_add_f32_e32 v6, v6, v28
	s_waitcnt vmcnt(6)
	v_add_f32_e32 v6, v6, v29
	s_waitcnt vmcnt(5)
	v_add_f32_e32 v6, v6, v30
	s_waitcnt vmcnt(4)
	v_add_f32_e32 v6, v6, v31
	s_waitcnt vmcnt(3)
	v_add_f32_e32 v6, v6, v32
	s_waitcnt vmcnt(2)
	v_add_f32_e32 v6, v6, v33
	s_waitcnt vmcnt(1)
	v_add_f32_e32 v6, v6, v34
	s_waitcnt vmcnt(0)
	v_add_f32_e32 v6, v6, v35
	ds_write_b32 v4, v6
	s_waitcnt lgkmcnt(0)
	s_barrier
	s_and_saveexec_b64 s[0:1], s[6:7]
	s_cbranch_execz .LBB0_462
	ds_read_b32 v6, v5
	ds_read_b32 v7, v4 offset:1024
	s_mov_b32 s2, 0x800000
	s_waitcnt lgkmcnt(0)
	v_add_f32_e32 v6, v6, v7
	v_fmamk_f32 v6, v6, 0x3a000000, v192
	v_mul_f32_e32 v7, 0x4b800000, v6
	v_cmp_gt_f32_e32 vcc, s2, v6
	s_nop 1
	v_cndmask_b32_e32 v6, v6, v7, vcc
	v_rsq_f32_e32 v6, v6
	s_nop 0
	v_mul_f32_e32 v7, 0x45800000, v6
	v_cndmask_b32_e32 v6, v6, v7, vcc
	ds_write_b32 v1, v6 offset:2048

; template <class Sched>
; __device__ __forceinline__ RsTable rs_prepass(PG8_LAS unsigned char* lds_spare, const float* ssp, const Sched& S, int tid) {
;     ...
;         if (T.pm[k] < 0) continue;
;         const float* p = ssp + (size_t)(16 * half) * 16384 + T.pm[k] * 256 + row; float s = 0.f;
; #pragma unroll
;         for (int q = 0; q < 16; ++q) s += p[(size_t)q * 16384];
;         part[half * 256 + row] = s;
;         __syncthreads();
;         if (half == 0) tab[k * 256 + row] = rsqrtf((part[row] + part[256 + row]) * (1.0f / 2048.0f) + 1e-6f);
;         __syncthreads();
.LBB0_464:
	s_lshl_b32 s56, s14, 8
	v_lshl_add_u64 v[6:7], s[56:57], 2, v[2:3]
	global_load_dword v20, v[6:7], off
	v_add_co_u32_e32 v36, vcc, 0x10000, v6
	s_nop 1
	v_addc_co_u32_e32 v37, vcc, 0, v7, vcc
	global_load_dword v21, v[36:37], off
	v_add_co_u32_e32 v36, vcc, 0x20000, v6
	s_nop 1
	v_addc_co_u32_e32 v37, vcc, 0, v7, vcc
	global_load_dword v22, v[36:37], off
	v_add_co_u32_e32 v36, vcc, 0x30000, v6
	s_nop 1
	v_addc_co_u32_e32 v37, vcc, 0, v7, vcc
	global_load_dword v23, v[36:37], off
	v_add_co_u32_e32 v36, vcc, 0x40000, v6
	s_nop 1
	v_addc_co_u32_e32 v37, vcc, 0, v7, vcc
	global_load_dword v24, v[36:37], off
	v_add_co_u32_e32 v36, vcc, 0x50000, v6
	s_nop 1
	v_addc_co_u32_e32 v37, vcc, 0, v7, vcc
	global_load_dword v25, v[36:37], off
	v_add_co_u32_e32 v36, vcc, 0x60000, v6
	s_nop 1
	v_addc_co_u32_e32 v37, vcc, 0, v7, vcc
	global_load_dword v26, v[36:37], off
	v_add_co_u32_e32 v36, vcc, 0x70000, v6
	s_nop 1
	v_addc_co_u32_e32 v37, vcc, 0, v7, vcc
	global_load_dword v27, v[36:37], off
	v_add_co_u32_e32 v36, vcc, 0x80000, v6
	s_nop 1
	v_addc_co_u32_e32 v37, vcc, 0, v7, vcc
	global_load_dword v28, v[36:37], off
	v_add_co_u32_e32 v36, vcc, 0x90000, v6
	s_nop 1
	v_addc_co_u32_e32 v37, vcc, 0, v7, vcc
	global_load_dword v29, v[36:37], off
	v_add_co_u32_e32 v36, vcc, 0xa0000, v6
	s_nop 1
	v_addc_co_u32_e32 v37, vcc, 0, v7, vcc
	global_load_dword v30, v[36:37], off
	v_add_co_u32_e32 v36, vcc, 0xb0000, v6
	s_nop 1
	v_addc_co_u32_e32 v37, vcc, 0, v7, vcc
	global_load_dword v31, v[36:37], off
	v_add_co_u32_e32 v36, vcc, 0xc0000, v6
	s_nop 1
	v_addc_co_u32_e32 v37, vcc, 0, v7, vcc
	global_load_dword v32, v[36:37], off
	v_add_co_u32_e32 v36, vcc, 0xd0000, v6
	s_nop 1
	v_addc_co_u32_e32 v37, vcc, 0, v7, vcc
	global_load_dword v33, v[36:37], off
	v_add_co_u32_e32 v36, vcc, 0xe0000, v6
	s_nop 1
	v_addc_co_u32_e32 v37, vcc, 0, v7, vcc
	global_load_dword v34, v[36:37], off
	v_add_co_u32_e32 v36, vcc, 0xf0000, v6
	s_nop 1
	v_addc_co_u32_e32 v37, vcc, 0, v7, vcc
	global_load_dword v35, v[36:37], off
	s_waitcnt vmcnt(15)
	v_add_f32_e32 v6, 0, v20
	s_waitcnt vmcnt(14)
	v_add_f32_e32 v6, v6, v21
	s_waitcnt vmcnt(13)
	v_add_f32_e32 v6, v6, v22
	s_waitcnt vmcnt(12)
	v_add_f32_e32 v6, v6, v23
	s_waitcnt vmcnt(11)
	v_add_f32_e32 v6, v6, v24
	s_waitcnt vmcnt(10)
	v_add_f32_e32 v6, v6, v25
	s_waitcnt vmcnt(9)
	v_add_f32_e32 v6, v6, v26
	s_waitcnt vmcnt(8)
	v_add_f32_e32 v6, v6, v27
	s_waitcnt vmcnt(7)
	v_add_f32_e32 v6, v6, v28
	s_waitcnt vmcnt(6)
	v_add_f32_e32 v6, v6, v29
	s_waitcnt vmcnt(5)
	v_add_f32_e32 v6, v6, v30
	s_waitcnt vmcnt(4)
	v_add_f32_e32 v6, v6, v31
	s_waitcnt vmcnt(3)
	v_add_f32_e32 v6, v6, v32
	s_waitcnt vmcnt(2)
	v_add_f32_e32 v6, v6, v33
	s_waitcnt vmcnt(1)
	v_add_f32_e32 v6, v6, v34
	s_waitcnt vmcnt(0)
	v_add_f32_e32 v6, v6, v35
	ds_write_b32 v4, v6
	s_waitcnt lgkmcnt(0)
	s_barrier
	s_and_saveexec_b64 s[0:1], s[6:7]
	s_cbranch_execz .LBB0_466
	ds_read_b32 v6, v5
	ds_read_b32 v7, v4 offset:1024
	s_mov_b32 s2, 0x800000
	s_waitcnt lgkmcnt(0)
	v_add_f32_e32 v6, v6, v7
	v_fmamk_f32 v6, v6, 0x3a000000, v192
	v_mul_f32_e32 v7, 0x4b800000, v6
	v_cmp_gt_f32_e32 vcc, s2, v6
	s_nop 1
	v_cndmask_b32_e32 v6, v6, v7, vcc
	v_rsq_f32_e32 v6, v6
	s_nop 0
	v_mul_f32_e32 v7, 0x45800000, v6
	v_cndmask_b32_e32 v6, v6, v7, vcc
	ds_write_b32 v1, v6 offset:1024

; template <class Sched>
; __device__ __forceinline__ RsTable rs_prepass(PG8_LAS unsigned char* lds_spare, const float* ssp, const Sched& S, int tid) {
;     ...
;         if (T.pm[k] < 0) continue;
;         const float* p = ssp + (size_t)(16 * half) * 16384 + T.pm[k] * 256 + row; float s = 0.f;
; #pragma unroll
;         for (int q = 0; q < 16; ++q) s += p[(size_t)q * 16384];
;         part[half * 256 + row] = s;
;         __syncthreads();
;         if (half == 0) tab[k * 256 + row] = rsqrtf((part[row] + part[256 + row]) * (1.0f / 2048.0f) + 1e-6f);
;         __syncthreads();
.LBB0_468:
	s_lshl_b32 s56, s8, 8
	v_lshl_add_u64 v[2:3], s[56:57], 2, v[2:3]
	global_load_dword v20, v[2:3], off
	v_add_co_u32_e32 v36, vcc, 0x10000, v2
	s_nop 1
	v_addc_co_u32_e32 v37, vcc, 0, v3, vcc
	global_load_dword v21, v[36:37], off
	v_add_co_u32_e32 v36, vcc, 0x20000, v2
	s_nop 1
	v_addc_co_u32_e32 v37, vcc, 0, v3, vcc
	global_load_dword v22, v[36:37], off
	v_add_co_u32_e32 v36, vcc, 0x30000, v2
	s_nop 1
	v_addc_co_u32_e32 v37, vcc, 0, v3, vcc
	global_load_dword v23, v[36:37], off
	v_add_co_u32_e32 v36, vcc, 0x40000, v2
	s_nop 1
	v_addc_co_u32_e32 v37, vcc, 0, v3, vcc
	global_load_dword v24, v[36:37], off
	v_add_co_u32_e32 v36, vcc, 0x50000, v2
	s_nop 1
	v_addc_co_u32_e32 v37, vcc, 0, v3, vcc
	global_load_dword v25, v[36:37], off
	v_add_co_u32_e32 v36, vcc, 0x60000, v2
	s_nop 1
	v_addc_co_u32_e32 v37, vcc, 0, v3, vcc
	global_load_dword v26, v[36:37], off
	v_add_co_u32_e32 v36, vcc, 0x70000, v2
	s_nop 1
	v_addc_co_u32_e32 v37, vcc, 0, v3, vcc
	global_load_dword v27, v[36:37], off
	v_add_co_u32_e32 v36, vcc, 0x80000, v2
	s_nop 1
	v_addc_co_u32_e32 v37, vcc, 0, v3, vcc
	global_load_dword v28, v[36:37], off
	v_add_co_u32_e32 v36, vcc, 0x90000, v2
	s_nop 1
	v_addc_co_u32_e32 v37, vcc, 0, v3, vcc
	global_load_dword v29, v[36:37], off
	v_add_co_u32_e32 v36, vcc, 0xa0000, v2
	s_nop 1
	v_addc_co_u32_e32 v37, vcc, 0, v3, vcc
	global_load_dword v30, v[36:37], off
	v_add_co_u32_e32 v36, vcc, 0xb0000, v2
	s_nop 1
	v_addc_co_u32_e32 v37, vcc, 0, v3, vcc
	global_load_dword v31, v[36:37], off
	v_add_co_u32_e32 v36, vcc, 0xc0000, v2
	s_nop 1
	v_addc_co_u32_e32 v37, vcc, 0, v3, vcc
	global_load_dword v32, v[36:37], off
	v_add_co_u32_e32 v36, vcc, 0xd0000, v2
	s_nop 1
	v_addc_co_u32_e32 v37, vcc, 0, v3, vcc
	global_load_dword v33, v[36:37], off
	v_add_co_u32_e32 v36, vcc, 0xe0000, v2
	s_nop 1
	v_addc_co_u32_e32 v37, vcc, 0, v3, vcc
	global_load_dword v34, v[36:37], off
	v_add_co_u32_e32 v36, vcc, 0xf0000, v2
	s_nop 1
	v_addc_co_u32_e32 v37, vcc, 0, v3, vcc
	global_load_dword v35, v[36:37], off
	s_waitcnt vmcnt(15)
	v_add_f32_e32 v2, 0, v20
	s_waitcnt vmcnt(14)
	v_add_f32_e32 v2, v2, v21
	s_waitcnt vmcnt(13)
	v_add_f32_e32 v2, v2, v22
	s_waitcnt vmcnt(12)
	v_add_f32_e32 v2, v2, v23
	s_waitcnt vmcnt(11)
	v_add_f32_e32 v2, v2, v24
	s_waitcnt vmcnt(10)
	v_add_f32_e32 v2, v2, v25
	s_waitcnt vmcnt(9)
	v_add_f32_e32 v2, v2, v26
	s_waitcnt vmcnt(8)
	v_add_f32_e32 v2, v2, v27
	s_waitcnt vmcnt(7)
	v_add_f32_e32 v2, v2, v28
	s_waitcnt vmcnt(6)
	v_add_f32_e32 v2, v2, v29
	s_waitcnt vmcnt(5)
	v_add_f32_e32 v2, v2, v30
	s_waitcnt vmcnt(4)
	v_add_f32_e32 v2, v2, v31
	s_waitcnt vmcnt(3)
	v_add_f32_e32 v2, v2, v32
	s_waitcnt vmcnt(2)
	v_add_f32_e32 v2, v2, v33
	s_waitcnt vmcnt(1)
	v_add_f32_e32 v2, v2, v34
	s_waitcnt vmcnt(0)
	v_add_f32_e32 v2, v2, v35
	ds_write_b32 v4, v2
	s_waitcnt lgkmcnt(0)
	s_barrier
	s_and_saveexec_b64 s[0:1], s[6:7]
	s_cbranch_execz .LBB0_470
	ds_read_b32 v2, v5
	ds_read_b32 v3, v4 offset:1024
	s_mov_b32 s2, 0x800000
	s_waitcnt lgkmcnt(0)
	v_add_f32_e32 v2, v2, v3
	v_fmamk_f32 v2, v2, 0x3a000000, v192
	v_mul_f32_e32 v3, 0x4b800000, v2
	v_cmp_gt_f32_e32 vcc, s2, v2
	s_nop 1
	v_cndmask_b32_e32 v2, v2, v3, vcc
	v_rsq_f32_e32 v2, v2
	s_nop 0
	v_mul_f32_e32 v3, 0x45800000, v2
	v_cndmask_b32_e32 v2, v2, v3, vcc
	ds_write_b32 v1, v2 offset:3072

; template <class Sched>
; __device__ __forceinline__ RsTable rs_prepass(PG8_LAS unsigned char* lds_spare, const float* ssp, const Sched& S, int tid) {
;     ...
;     const int row = tid & 255, half = tid >> 8;
; #pragma unroll
;     for (int k = 0; k < 4; ++k) {
;         if (T.pm[k] < 0) continue;
;         const float* p = ssp + (size_t)(16 * half) * 16384 + T.pm[k] * 256 + row; float s = 0.f;
; #pragma unroll
;         for (int q = 0; q < 16; ++q) s += p[(size_t)q * 16384];
;         part[half * 256 + row] = s;
;         __syncthreads();
;         if (half == 0) tab[k * 256 + row] = rsqrtf((part[row] + part[256 + row]) * (1.0f / 2048.0f) + 1e-6f);
;         __syncthreads();
; __device__ __forceinline__ void final_tiles(LAS unsigned char* lds, const bf16* XB, const float* ss, const float* g, float* OF, int G, int bx, int tid) {
;     pg8::StaticOrder S; S.init(M, DM, G, bx, WGM_DN); pg8::Unit u;
;     const pg8::RsTable T = pg8::rs_prepass(lds + 131072, ss, S, tid);
.LBB0_626:
	v_lshl_add_u32 v1, s16, 6, v4
	v_ashrrev_i32_e32 v2, 4, v1
	v_and_b32_e32 v2, -16, v2
	v_ashrrev_i32_e32 v3, 31, v2
	v_lshlrev_b64 v[2:3], 16, v[2:3]
	v_lshl_add_u64 v[2:3], s[0:1], 0, v[2:3]
	v_lshlrev_b32_sdwa v8, v198, v1 dst_sel:DWORD dst_unused:UNUSED_PAD src0_sel:DWORD src1_sel:BYTE_0
	v_mov_b32_e32 v9, v0
	v_lshlrev_b32_e32 v6, 2, v1
	v_readlane_b32 s2, v251, 23
	v_lshl_add_u64 v[2:3], v[2:3], 0, v[8:9]
	s_mov_b64 s[0:1], 0x1fe00000
	v_readlane_b32 s20, v252, 5
	v_add_u32_e32 v5, s2, v6
	v_lshl_add_u64 v[2:3], v[2:3], 0, s[0:1]
	v_readlane_b32 s2, v251, 24
	s_movk_i32 s0, 0x100
	v_readlane_b32 s22, v252, 7
	v_readlane_b32 s23, v252, 8
	v_readlane_b32 s26, v252, 11
	v_readlane_b32 s27, v252, 12
	v_add_u32_e32 v6, s2, v6
	v_cmp_gt_u32_e64 s[0:1], s0, v1
	s_cmp_gt_i32 s17, -1
	v_add_u32_e32 v7, s2, v8
	s_mov_b64 s[22:23], s[26:27]
	s_mov_b32 s16, 0x800000
	v_readlane_b32 s21, v252, 6
	v_readlane_b32 s24, v252, 9
	v_readlane_b32 s25, v252, 10
	s_cbranch_scc0 .LBB0_630
	s_lshl_b32 s56, s17, 8
	v_lshl_add_u64 v[8:9], s[56:57], 2, v[2:3]
	global_load_dword v20, v[8:9], off
	v_add_co_u32_e32 v36, vcc, 0x10000, v8
	s_nop 1
	v_addc_co_u32_e32 v37, vcc, 0, v9, vcc
	global_load_dword v21, v[36:37], off
	v_add_co_u32_e32 v36, vcc, 0x20000, v8
	s_nop 1
	v_addc_co_u32_e32 v37, vcc, 0, v9, vcc
	global_load_dword v22, v[36:37], off
	v_add_co_u32_e32 v36, vcc, 0x30000, v8
	s_nop 1
	v_addc_co_u32_e32 v37, vcc, 0, v9, vcc
	global_load_dword v23, v[36:37], off
	v_add_co_u32_e32 v36, vcc, 0x40000, v8
	s_nop 1
	v_addc_co_u32_e32 v37, vcc, 0, v9, vcc
	global_load_dword v24, v[36:37], off
	v_add_co_u32_e32 v36, vcc, 0x50000, v8
	s_nop 1
	v_addc_co_u32_e32 v37, vcc, 0, v9, vcc
	global_load_dword v25, v[36:37], off
	v_add_co_u32_e32 v36, vcc, 0x60000, v8
	s_nop 1
	v_addc_co_u32_e32 v37, vcc, 0, v9, vcc
	global_load_dword v26, v[36:37], off
	v_add_co_u32_e32 v36, vcc, 0x70000, v8
	s_nop 1
	v_addc_co_u32_e32 v37, vcc, 0, v9, vcc
	global_load_dword v27, v[36:37], off
	v_add_co_u32_e32 v36, vcc, 0x80000, v8
	s_nop 1
	v_addc_co_u32_e32 v37, vcc, 0, v9, vcc
	global_load_dword v28, v[36:37], off
	v_add_co_u32_e32 v36, vcc, 0x90000, v8
	s_nop 1
	v_addc_co_u32_e32 v37, vcc, 0, v9, vcc
	global_load_dword v29, v[36:37], off
	v_add_co_u32_e32 v36, vcc, 0xa0000, v8
	s_nop 1
	v_addc_co_u32_e32 v37, vcc, 0, v9, vcc
	global_load_dword v30, v[36:37], off
	v_add_co_u32_e32 v36, vcc, 0xb0000, v8
	s_nop 1
	v_addc_co_u32_e32 v37, vcc, 0, v9, vcc
	global_load_dword v31, v[36:37], off
	v_add_co_u32_e32 v36, vcc, 0xc0000, v8
	s_nop 1
	v_addc_co_u32_e32 v37, vcc, 0, v9, vcc
	global_load_dword v32, v[36:37], off
	v_add_co_u32_e32 v36, vcc, 0xd0000, v8
	s_nop 1
	v_addc_co_u32_e32 v37, vcc, 0, v9, vcc
	global_load_dword v33, v[36:37], off
	v_add_co_u32_e32 v36, vcc, 0xe0000, v8
	s_nop 1
	v_addc_co_u32_e32 v37, vcc, 0, v9, vcc
	global_load_dword v34, v[36:37], off
	v_add_co_u32_e32 v36, vcc, 0xf0000, v8
	s_nop 1
	v_addc_co_u32_e32 v37, vcc, 0, v9, vcc
	global_load_dword v35, v[36:37], off
	s_waitcnt vmcnt(15)
	v_add_f32_e32 v8, 0, v20
	s_waitcnt vmcnt(14)
	v_add_f32_e32 v8, v8, v21
	s_waitcnt vmcnt(13)
	v_add_f32_e32 v8, v8, v22
	s_waitcnt vmcnt(12)
	v_add_f32_e32 v8, v8, v23
	s_waitcnt vmcnt(11)
	v_add_f32_e32 v8, v8, v24
	s_waitcnt vmcnt(10)
	v_add_f32_e32 v8, v8, v25
	s_waitcnt vmcnt(9)
	v_add_f32_e32 v8, v8, v26
	s_waitcnt vmcnt(8)
	v_add_f32_e32 v8, v8, v27
	s_waitcnt vmcnt(7)
	v_add_f32_e32 v8, v8, v28
	s_waitcnt vmcnt(6)
	v_add_f32_e32 v8, v8, v29
	s_waitcnt vmcnt(5)
	v_add_f32_e32 v8, v8, v30
	s_waitcnt vmcnt(4)
	v_add_f32_e32 v8, v8, v31
	s_waitcnt vmcnt(3)
	v_add_f32_e32 v8, v8, v32
	s_waitcnt vmcnt(2)
	v_add_f32_e32 v8, v8, v33
	s_waitcnt vmcnt(1)
	v_add_f32_e32 v8, v8, v34
	s_waitcnt vmcnt(0)
	v_add_f32_e32 v8, v8, v35
	ds_write_b32 v6, v8
	s_waitcnt lgkmcnt(0)
	s_barrier
	s_and_saveexec_b64 s[2:3], s[0:1]
	s_cbranch_execz .LBB0_629
	ds_read_b32 v8, v7
	ds_read_b32 v9, v6 offset:1024
	s_waitcnt lgkmcnt(0)
	v_add_f32_e32 v8, v8, v9
	v_fmamk_f32 v8, v8, 0x3a000000, v192
	v_mul_f32_e32 v9, 0x4b800000, v8
	v_cmp_gt_f32_e32 vcc, s16, v8
	s_nop 1
	v_cndmask_b32_e32 v8, v8, v9, vcc
	v_rsq_f32_e32 v8, v8
	s_nop 0
	v_mul_f32_e32 v9, 0x45800000, v8
	v_cndmask_b32_e32 v8, v8, v9, vcc
	ds_write_b32 v5, v8

; template <class Sched>
; __device__ __forceinline__ RsTable rs_prepass(PG8_LAS unsigned char* lds_spare, const float* ssp, const Sched& S, int tid) {
;     ...
;         if (T.pm[k] < 0) continue;
;         const float* p = ssp + (size_t)(16 * half) * 16384 + T.pm[k] * 256 + row; float s = 0.f;
; #pragma unroll
;         for (int q = 0; q < 16; ++q) s += p[(size_t)q * 16384];
;         part[half * 256 + row] = s;
;         __syncthreads();
;         if (half == 0) tab[k * 256 + row] = rsqrtf((part[row] + part[256 + row]) * (1.0f / 2048.0f) + 1e-6f);
;         __syncthreads();
.LBB0_630:
	s_cmp_lt_i32 s15, 0
	v_readlane_b32 s24, v251, 46
	s_cbranch_scc1 .LBB0_635
	s_lshl_b32 s56, s15, 8
	v_lshl_add_u64 v[8:9], s[56:57], 2, v[2:3]
	global_load_dword v20, v[8:9], off
	v_add_co_u32_e32 v36, vcc, 0x10000, v8
	s_nop 1
	v_addc_co_u32_e32 v37, vcc, 0, v9, vcc
	global_load_dword v21, v[36:37], off
	v_add_co_u32_e32 v36, vcc, 0x20000, v8
	s_nop 1
	v_addc_co_u32_e32 v37, vcc, 0, v9, vcc
	global_load_dword v22, v[36:37], off
	v_add_co_u32_e32 v36, vcc, 0x30000, v8
	s_nop 1
	v_addc_co_u32_e32 v37, vcc, 0, v9, vcc
	global_load_dword v23, v[36:37], off
	v_add_co_u32_e32 v36, vcc, 0x40000, v8
	s_nop 1
	v_addc_co_u32_e32 v37, vcc, 0, v9, vcc
	global_load_dword v24, v[36:37], off
	v_add_co_u32_e32 v36, vcc, 0x50000, v8
	s_nop 1
	v_addc_co_u32_e32 v37, vcc, 0, v9, vcc
	global_load_dword v25, v[36:37], off
	v_add_co_u32_e32 v36, vcc, 0x60000, v8
	s_nop 1
	v_addc_co_u32_e32 v37, vcc, 0, v9, vcc
	global_load_dword v26, v[36:37], off
	v_add_co_u32_e32 v36, vcc, 0x70000, v8
	s_nop 1
	v_addc_co_u32_e32 v37, vcc, 0, v9, vcc
	global_load_dword v27, v[36:37], off
	v_add_co_u32_e32 v36, vcc, 0x80000, v8
	s_nop 1
	v_addc_co_u32_e32 v37, vcc, 0, v9, vcc
	global_load_dword v28, v[36:37], off
	v_add_co_u32_e32 v36, vcc, 0x90000, v8
	s_nop 1
	v_addc_co_u32_e32 v37, vcc, 0, v9, vcc
	global_load_dword v29, v[36:37], off
	v_add_co_u32_e32 v36, vcc, 0xa0000, v8
	s_nop 1
	v_addc_co_u32_e32 v37, vcc, 0, v9, vcc
	global_load_dword v30, v[36:37], off
	v_add_co_u32_e32 v36, vcc, 0xb0000, v8
	s_nop 1
	v_addc_co_u32_e32 v37, vcc, 0, v9, vcc
	global_load_dword v31, v[36:37], off
	v_add_co_u32_e32 v36, vcc, 0xc0000, v8
	s_nop 1
	v_addc_co_u32_e32 v37, vcc, 0, v9, vcc
	global_load_dword v32, v[36:37], off
	v_add_co_u32_e32 v36, vcc, 0xd0000, v8
	s_nop 1
	v_addc_co_u32_e32 v37, vcc, 0, v9, vcc
	global_load_dword v33, v[36:37], off
	v_add_co_u32_e32 v36, vcc, 0xe0000, v8
	s_nop 1
	v_addc_co_u32_e32 v37, vcc, 0, v9, vcc
	global_load_dword v34, v[36:37], off
	v_add_co_u32_e32 v36, vcc, 0xf0000, v8
	s_nop 1
	v_addc_co_u32_e32 v37, vcc, 0, v9, vcc
	global_load_dword v35, v[36:37], off
	s_waitcnt vmcnt(15)
	v_add_f32_e32 v8, 0, v20
	s_waitcnt vmcnt(14)
	v_add_f32_e32 v8, v8, v21
	s_waitcnt vmcnt(13)
	v_add_f32_e32 v8, v8, v22
	s_waitcnt vmcnt(12)
	v_add_f32_e32 v8, v8, v23
	s_waitcnt vmcnt(11)
	v_add_f32_e32 v8, v8, v24
	s_waitcnt vmcnt(10)
	v_add_f32_e32 v8, v8, v25
	s_waitcnt vmcnt(9)
	v_add_f32_e32 v8, v8, v26
	s_waitcnt vmcnt(8)
	v_add_f32_e32 v8, v8, v27
	s_waitcnt vmcnt(7)
	v_add_f32_e32 v8, v8, v28
	s_waitcnt vmcnt(6)
	v_add_f32_e32 v8, v8, v29
	s_waitcnt vmcnt(5)
	v_add_f32_e32 v8, v8, v30
	s_waitcnt vmcnt(4)
	v_add_f32_e32 v8, v8, v31
	s_waitcnt vmcnt(3)
	v_add_f32_e32 v8, v8, v32
	s_waitcnt vmcnt(2)
	v_add_f32_e32 v8, v8, v33
	s_waitcnt vmcnt(1)
	v_add_f32_e32 v8, v8, v34
	s_waitcnt vmcnt(0)
	v_add_f32_e32 v8, v8, v35
	ds_write_b32 v6, v8
	s_waitcnt lgkmcnt(0)
	s_barrier
	s_and_saveexec_b64 s[2:3], s[0:1]
	s_cbranch_execz .LBB0_633
	ds_read_b32 v8, v7
	ds_read_b32 v9, v6 offset:1024
	s_waitcnt lgkmcnt(0)
	v_add_f32_e32 v8, v8, v9
	v_fmamk_f32 v8, v8, 0x3a000000, v192
	v_mul_f32_e32 v9, 0x4b800000, v8
	v_cmp_gt_f32_e32 vcc, s16, v8
	s_nop 1
	v_cndmask_b32_e32 v8, v8, v9, vcc
	v_rsq_f32_e32 v8, v8
	s_nop 0
	v_mul_f32_e32 v9, 0x45800000, v8
	v_cndmask_b32_e32 v8, v8, v9, vcc
	ds_write_b32 v5, v8 offset:1024

; template <class Sched>
; __device__ __forceinline__ RsTable rs_prepass(PG8_LAS unsigned char* lds_spare, const float* ssp, const Sched& S, int tid) {
;     ...
;         if (T.pm[k] < 0) continue;
;         const float* p = ssp + (size_t)(16 * half) * 16384 + T.pm[k] * 256 + row; float s = 0.f;
; #pragma unroll
;         for (int q = 0; q < 16; ++q) s += p[(size_t)q * 16384];
;         part[half * 256 + row] = s;
;         __syncthreads();
;         if (half == 0) tab[k * 256 + row] = rsqrtf((part[row] + part[256 + row]) * (1.0f / 2048.0f) + 1e-6f);
;         __syncthreads();
.LBB0_636:
	s_lshl_b32 s56, s14, 8
	v_lshl_add_u64 v[8:9], s[56:57], 2, v[2:3]
	global_load_dword v20, v[8:9], off
	v_add_co_u32_e32 v36, vcc, 0x10000, v8
	s_nop 1
	v_addc_co_u32_e32 v37, vcc, 0, v9, vcc
	global_load_dword v21, v[36:37], off
	v_add_co_u32_e32 v36, vcc, 0x20000, v8
	s_nop 1
	v_addc_co_u32_e32 v37, vcc, 0, v9, vcc
	global_load_dword v22, v[36:37], off
	v_add_co_u32_e32 v36, vcc, 0x30000, v8
	s_nop 1
	v_addc_co_u32_e32 v37, vcc, 0, v9, vcc
	global_load_dword v23, v[36:37], off
	v_add_co_u32_e32 v36, vcc, 0x40000, v8
	s_nop 1
	v_addc_co_u32_e32 v37, vcc, 0, v9, vcc
	global_load_dword v24, v[36:37], off
	v_add_co_u32_e32 v36, vcc, 0x50000, v8
	s_nop 1
	v_addc_co_u32_e32 v37, vcc, 0, v9, vcc
	global_load_dword v25, v[36:37], off
	v_add_co_u32_e32 v36, vcc, 0x60000, v8
	s_nop 1
	v_addc_co_u32_e32 v37, vcc, 0, v9, vcc
	global_load_dword v26, v[36:37], off
	v_add_co_u32_e32 v36, vcc, 0x70000, v8
	s_nop 1
	v_addc_co_u32_e32 v37, vcc, 0, v9, vcc
	global_load_dword v27, v[36:37], off
	v_add_co_u32_e32 v36, vcc, 0x80000, v8
	s_nop 1
	v_addc_co_u32_e32 v37, vcc, 0, v9, vcc
	global_load_dword v28, v[36:37], off
	v_add_co_u32_e32 v36, vcc, 0x90000, v8
	s_nop 1
	v_addc_co_u32_e32 v37, vcc, 0, v9, vcc
	global_load_dword v29, v[36:37], off
	v_add_co_u32_e32 v36, vcc, 0xa0000, v8
	s_nop 1
	v_addc_co_u32_e32 v37, vcc, 0, v9, vcc
	global_load_dword v30, v[36:37], off
	v_add_co_u32_e32 v36, vcc, 0xb0000, v8
	s_nop 1
	v_addc_co_u32_e32 v37, vcc, 0, v9, vcc
	global_load_dword v31, v[36:37], off
	v_add_co_u32_e32 v36, vcc, 0xc0000, v8
	s_nop 1
	v_addc_co_u32_e32 v37, vcc, 0, v9, vcc
	global_load_dword v32, v[36:37], off
	v_add_co_u32_e32 v36, vcc, 0xd0000, v8
	s_nop 1
	v_addc_co_u32_e32 v37, vcc, 0, v9, vcc
	global_load_dword v33, v[36:37], off
	v_add_co_u32_e32 v36, vcc, 0xe0000, v8
	s_nop 1
	v_addc_co_u32_e32 v37, vcc, 0, v9, vcc
	global_load_dword v34, v[36:37], off
	v_add_co_u32_e32 v36, vcc, 0xf0000, v8
	s_nop 1
	v_addc_co_u32_e32 v37, vcc, 0, v9, vcc
	global_load_dword v35, v[36:37], off
	s_waitcnt vmcnt(15)
	v_add_f32_e32 v8, 0, v20
	s_waitcnt vmcnt(14)
	v_add_f32_e32 v8, v8, v21
	s_waitcnt vmcnt(13)
	v_add_f32_e32 v8, v8, v22
	s_waitcnt vmcnt(12)
	v_add_f32_e32 v8, v8, v23
	s_waitcnt vmcnt(11)
	v_add_f32_e32 v8, v8, v24
	s_waitcnt vmcnt(10)
	v_add_f32_e32 v8, v8, v25
	s_waitcnt vmcnt(9)
	v_add_f32_e32 v8, v8, v26
	s_waitcnt vmcnt(8)
	v_add_f32_e32 v8, v8, v27
	s_waitcnt vmcnt(7)
	v_add_f32_e32 v8, v8, v28
	s_waitcnt vmcnt(6)
	v_add_f32_e32 v8, v8, v29
	s_waitcnt vmcnt(5)
	v_add_f32_e32 v8, v8, v30
	s_waitcnt vmcnt(4)
	v_add_f32_e32 v8, v8, v31
	s_waitcnt vmcnt(3)
	v_add_f32_e32 v8, v8, v32
	s_waitcnt vmcnt(2)
	v_add_f32_e32 v8, v8, v33
	s_waitcnt vmcnt(1)
	v_add_f32_e32 v8, v8, v34
	s_waitcnt vmcnt(0)
	v_add_f32_e32 v8, v8, v35
	ds_write_b32 v6, v8
	s_waitcnt lgkmcnt(0)
	s_barrier
	s_and_saveexec_b64 s[2:3], s[0:1]
	s_cbranch_execz .LBB0_638
	ds_read_b32 v8, v7
	ds_read_b32 v9, v6 offset:1024
	s_waitcnt lgkmcnt(0)
	v_add_f32_e32 v8, v8, v9
	v_fmamk_f32 v8, v8, 0x3a000000, v192
	v_mul_f32_e32 v9, 0x4b800000, v8
	v_cmp_gt_f32_e32 vcc, s16, v8
	s_nop 1
	v_cndmask_b32_e32 v8, v8, v9, vcc
	v_rsq_f32_e32 v8, v8
	s_nop 0
	v_mul_f32_e32 v9, 0x45800000, v8
	v_cndmask_b32_e32 v8, v8, v9, vcc
	ds_write_b32 v5, v8 offset:2048

; template <class Sched>
; __device__ __forceinline__ RsTable rs_prepass(PG8_LAS unsigned char* lds_spare, const float* ssp, const Sched& S, int tid) {
;     ...
;         const float* p = ssp + (size_t)(16 * half) * 16384 + T.pm[k] * 256 + row; float s = 0.f;
; #pragma unroll
;         for (int q = 0; q < 16; ++q) s += p[(size_t)q * 16384];
;         part[half * 256 + row] = s;
;         __syncthreads();
;         if (half == 0) tab[k * 256 + row] = rsqrtf((part[row] + part[256 + row]) * (1.0f / 2048.0f) + 1e-6f);
.LBB0_639:
	s_lshl_b32 s56, s13, 8
	v_lshl_add_u64 v[2:3], s[56:57], 2, v[2:3]
	global_load_dword v20, v[2:3], off
	v_add_co_u32_e32 v36, vcc, 0x10000, v2
	s_nop 1
	v_addc_co_u32_e32 v37, vcc, 0, v3, vcc
	global_load_dword v21, v[36:37], off
	v_add_co_u32_e32 v36, vcc, 0x20000, v2
	s_nop 1
	v_addc_co_u32_e32 v37, vcc, 0, v3, vcc
	global_load_dword v22, v[36:37], off
	v_add_co_u32_e32 v36, vcc, 0x30000, v2
	s_nop 1
	v_addc_co_u32_e32 v37, vcc, 0, v3, vcc
	global_load_dword v23, v[36:37], off
	v_add_co_u32_e32 v36, vcc, 0x40000, v2
	s_nop 1
	v_addc_co_u32_e32 v37, vcc, 0, v3, vcc
	global_load_dword v24, v[36:37], off
	v_add_co_u32_e32 v36, vcc, 0x50000, v2
	s_nop 1
	v_addc_co_u32_e32 v37, vcc, 0, v3, vcc
	global_load_dword v25, v[36:37], off
	v_add_co_u32_e32 v36, vcc, 0x60000, v2
	s_nop 1
	v_addc_co_u32_e32 v37, vcc, 0, v3, vcc
	global_load_dword v26, v[36:37], off
	v_add_co_u32_e32 v36, vcc, 0x70000, v2
	s_nop 1
	v_addc_co_u32_e32 v37, vcc, 0, v3, vcc
	global_load_dword v27, v[36:37], off
	v_add_co_u32_e32 v36, vcc, 0x80000, v2
	s_nop 1
	v_addc_co_u32_e32 v37, vcc, 0, v3, vcc
	global_load_dword v28, v[36:37], off
	v_add_co_u32_e32 v36, vcc, 0x90000, v2
	s_nop 1
	v_addc_co_u32_e32 v37, vcc, 0, v3, vcc
	global_load_dword v29, v[36:37], off
	v_add_co_u32_e32 v36, vcc, 0xa0000, v2
	s_nop 1
	v_addc_co_u32_e32 v37, vcc, 0, v3, vcc
	global_load_dword v30, v[36:37], off
	v_add_co_u32_e32 v36, vcc, 0xb0000, v2
	s_nop 1
	v_addc_co_u32_e32 v37, vcc, 0, v3, vcc
	global_load_dword v31, v[36:37], off
	v_add_co_u32_e32 v36, vcc, 0xc0000, v2
	s_nop 1
	v_addc_co_u32_e32 v37, vcc, 0, v3, vcc
	global_load_dword v32, v[36:37], off
	v_add_co_u32_e32 v36, vcc, 0xd0000, v2
	s_nop 1
	v_addc_co_u32_e32 v37, vcc, 0, v3, vcc
	global_load_dword v33, v[36:37], off
	v_add_co_u32_e32 v36, vcc, 0xe0000, v2
	s_nop 1
	v_addc_co_u32_e32 v37, vcc, 0, v3, vcc
	global_load_dword v34, v[36:37], off
	v_add_co_u32_e32 v36, vcc, 0xf0000, v2
	s_nop 1
	v_addc_co_u32_e32 v37, vcc, 0, v3, vcc
	global_load_dword v35, v[36:37], off
	s_waitcnt vmcnt(15)
	v_add_f32_e32 v2, 0, v20
	s_waitcnt vmcnt(14)
	v_add_f32_e32 v2, v2, v21
	s_waitcnt vmcnt(13)
	v_add_f32_e32 v2, v2, v22
	s_waitcnt vmcnt(12)
	v_add_f32_e32 v2, v2, v23
	s_waitcnt vmcnt(11)
	v_add_f32_e32 v2, v2, v24
	s_waitcnt vmcnt(10)
	v_add_f32_e32 v2, v2, v25
	s_waitcnt vmcnt(9)
	v_add_f32_e32 v2, v2, v26
	s_waitcnt vmcnt(8)
	v_add_f32_e32 v2, v2, v27
	s_waitcnt vmcnt(7)
	v_add_f32_e32 v2, v2, v28
	s_waitcnt vmcnt(6)
	v_add_f32_e32 v2, v2, v29
	s_waitcnt vmcnt(5)
	v_add_f32_e32 v2, v2, v30
	s_waitcnt vmcnt(4)
	v_add_f32_e32 v2, v2, v31
	s_waitcnt vmcnt(3)
	v_add_f32_e32 v2, v2, v32
	s_waitcnt vmcnt(2)
	v_add_f32_e32 v2, v2, v33
	s_waitcnt vmcnt(1)
	v_add_f32_e32 v2, v2, v34
	s_waitcnt vmcnt(0)
	v_add_f32_e32 v2, v2, v35
	ds_write_b32 v6, v2
	s_waitcnt lgkmcnt(0)
	s_barrier
	s_and_saveexec_b64 s[2:3], s[0:1]
	s_cbranch_execz .LBB0_641
	ds_read_b32 v2, v7
	ds_read_b32 v3, v6 offset:1024
	s_waitcnt lgkmcnt(0)
	v_add_f32_e32 v2, v2, v3
	v_fmamk_f32 v2, v2, 0x3a000000, v192
	v_mul_f32_e32 v3, 0x4b800000, v2
	v_cmp_gt_f32_e32 vcc, s16, v2
	s_nop 1
	v_cndmask_b32_e32 v2, v2, v3, vcc
	v_rsq_f32_e32 v2, v2
	s_nop 0
	v_mul_f32_e32 v3, 0x45800000, v2
	v_cndmask_b32_e32 v2, v2, v3, vcc
	ds_write_b32 v5, v2 offset:3072
